# attention: waves that run the trailing exp block after the half-step barrier do so at raised priority
# baseline (speedup 1.0000x reference)
.LBB0_1231:
	s_cmp_eq_u32 s100, 0
	s_cbranch_scc1 .Lblk2_a
	s_waitcnt lgkmcnt(0)
	s_barrier
	s_setprio 2
	v_cndmask_b32_e64 v201, v148, v156, s[40:41]
	v_mul_f32_e32 v206, 0xbe0293ee, v201
	v_fmamk_f32 v82, v82, 0x3e0293ee, v206
	v_fmamk_f32 v83, v83, 0x3e0293ee, v206
	v_fmamk_f32 v84, v84, 0x3e0293ee, v206
	v_fmamk_f32 v85, v85, 0x3e0293ee, v206
	v_fmamk_f32 v86, v86, 0x3e0293ee, v206
	v_fmamk_f32 v87, v87, 0x3e0293ee, v206
	v_fmamk_f32 v88, v88, 0x3e0293ee, v206
	v_fmamk_f32 v89, v89, 0x3e0293ee, v206
	v_fmamk_f32 v90, v90, 0x3e0293ee, v206
	v_fmamk_f32 v91, v91, 0x3e0293ee, v206
	v_fmamk_f32 v92, v92, 0x3e0293ee, v206
	v_fmamk_f32 v93, v93, 0x3e0293ee, v206
	v_fmamk_f32 v94, v94, 0x3e0293ee, v206
	v_fmamk_f32 v95, v95, 0x3e0293ee, v206
	v_fmamk_f32 v96, v96, 0x3e0293ee, v206
	v_fmamk_f32 v97, v97, 0x3e0293ee, v206
	v_exp_f32_e32 v148, v82
	v_exp_f32_e32 v163, v83
	v_exp_f32_e32 v149, v84
	v_exp_f32_e32 v162, v85
	v_exp_f32_e32 v150, v86
	v_exp_f32_e32 v161, v87
	v_exp_f32_e32 v151, v88
	v_exp_f32_e32 v160, v89
	v_exp_f32_e32 v152, v90
	v_exp_f32_e32 v159, v91
	v_exp_f32_e32 v153, v92
	v_exp_f32_e32 v158, v93
	v_exp_f32_e32 v154, v94
	v_exp_f32_e32 v157, v95
	v_exp_f32_e32 v155, v96
	v_exp_f32_e32 v156, v97
	v_fmamk_f32 v215, v66, 0x3e0293ee, v206
	v_fmamk_f32 v216, v67, 0x3e0293ee, v206
	v_fmamk_f32 v217, v68, 0x3e0293ee, v206
	v_fmamk_f32 v218, v69, 0x3e0293ee, v206
	v_fmamk_f32 v219, v70, 0x3e0293ee, v206
	v_fmamk_f32 v208, v71, 0x3e0293ee, v206
	v_fmamk_f32 v209, v72, 0x3e0293ee, v206
	v_fmamk_f32 v210, v73, 0x3e0293ee, v206
	v_fmamk_f32 v211, v74, 0x3e0293ee, v206
	v_fmamk_f32 v212, v75, 0x3e0293ee, v206
	v_fmamk_f32 v213, v76, 0x3e0293ee, v206
	v_fmamk_f32 v214, v77, 0x3e0293ee, v206
	v_fmamk_f32 v207, v78, 0x3e0293ee, v206
	v_fmamk_f32 v220, v79, 0x3e0293ee, v206
	v_fmamk_f32 v221, v80, 0x3e0293ee, v206
	v_fmac_f32_e32 v206, 0x3e0293ee, v81
	s_setprio 0
	s_branch .Lblk2_j

.LBB0_1241:
	s_cmp_eq_u32 s100, 0
	s_cbranch_scc1 .Lblk3_a
	s_waitcnt lgkmcnt(0)
	s_barrier
	s_setprio 2
	v_cndmask_b32_e64 v156, v132, v201, s[40:41]
	v_mul_f32_e32 v134, 0xbe0293ee, v156
	v_mov_b32_e32 v135, v134
	v_fmamk_f32 v82, v82, 0x3e0293ee, v134
	v_fmamk_f32 v83, v83, 0x3e0293ee, v134
	v_fmamk_f32 v84, v84, 0x3e0293ee, v134
	v_fmamk_f32 v85, v85, 0x3e0293ee, v134
	v_fmamk_f32 v86, v86, 0x3e0293ee, v134
	v_fmamk_f32 v87, v87, 0x3e0293ee, v134
	v_fmamk_f32 v88, v88, 0x3e0293ee, v134
	v_fmamk_f32 v89, v89, 0x3e0293ee, v134
	v_fmamk_f32 v90, v90, 0x3e0293ee, v134
	v_fmamk_f32 v91, v91, 0x3e0293ee, v134
	v_fmamk_f32 v92, v92, 0x3e0293ee, v134
	v_fmamk_f32 v93, v93, 0x3e0293ee, v134
	v_fmamk_f32 v94, v94, 0x3e0293ee, v134
	v_fmamk_f32 v95, v95, 0x3e0293ee, v134
	v_fmamk_f32 v96, v96, 0x3e0293ee, v134
	v_fmac_f32_e32 v135, 0x3e0293ee, v97
	v_exp_f32_e32 v163, v82
	v_exp_f32_e32 v177, v83
	v_exp_f32_e32 v149, v84
	v_exp_f32_e32 v176, v85
	v_exp_f32_e32 v150, v86
	v_exp_f32_e32 v162, v87
	v_exp_f32_e32 v151, v88
	v_exp_f32_e32 v161, v89
	v_exp_f32_e32 v152, v90
	v_exp_f32_e32 v160, v91
	v_exp_f32_e32 v153, v92
	v_exp_f32_e32 v159, v93
	v_exp_f32_e32 v154, v94
	v_exp_f32_e32 v158, v95
	v_exp_f32_e32 v155, v96
	v_exp_f32_e32 v157, v135
	s_waitcnt vmcnt(0)
	v_pk_fma_f32 v[144:145], v[66:67], s[36:37], v[134:135] op_sel_hi:[1,0,0]
	v_add_f32_e32 v66, v197, v198
	s_mov_b64 s[4:5], 0x8000
	v_fmac_f32_e32 v66, v194, v187
	v_add_f32_e32 v187, v206, v207
	s_addk_i32 s11, 0x80
	v_lshl_add_u64 v[172:173], v[172:173], 0, s[4:5]
	s_add_i32 s0, s0, 2
	s_mov_b64 s[4:5], 0x350000
	v_pk_fma_f32 v[142:143], v[68:69], s[36:37], v[134:135] op_sel_hi:[1,0,0]
	v_pk_fma_f32 v[138:139], v[70:71], s[36:37], v[134:135] op_sel_hi:[1,0,0]
	v_pk_fma_f32 v[136:137], v[72:73], s[36:37], v[134:135] op_sel_hi:[1,0,0]
	v_pk_fma_f32 v[132:133], v[74:75], s[36:37], v[134:135] op_sel_hi:[1,0,0]
	v_pk_fma_f32 v[146:147], v[76:77], s[36:37], v[134:135] op_sel_hi:[1,0,0]
	v_pk_fma_f32 v[140:141], v[78:79], s[36:37], v[134:135] op_sel_hi:[1,0,0]
	v_pk_fma_f32 v[134:135], v[80:81], s[36:37], v[134:135] op_sel_hi:[1,0,0]
	v_fmac_f32_e32 v187, v66, v199
	v_add_u32_e32 v195, 0x200, v195
	v_add_u32_e32 v196, 0xffffff80, v196
	s_cmp_lt_u32 s0, s35
	v_lshl_add_u64 v[174:175], v[174:175], 0, s[4:5]
	s_setprio 0
	s_branch .Lblk3_j

.LBB0_1392:
	s_cmp_eq_u32 s100, 0
	s_cbranch_scc1 .Lblk0_a
	s_waitcnt lgkmcnt(0)
	s_barrier
	s_setprio 2
	v_cndmask_b32_e64 v224, v168, v176, s[40:41]
	v_mul_f32_e32 v227, 0xbdd53b94, v224
	v_fmamk_f32 v82, v82, 0x3dd53b94, v227
	v_fmamk_f32 v83, v83, 0x3dd53b94, v227
	v_fmamk_f32 v84, v84, 0x3dd53b94, v227
	v_fmamk_f32 v85, v85, 0x3dd53b94, v227
	v_fmamk_f32 v86, v86, 0x3dd53b94, v227
	v_fmamk_f32 v87, v87, 0x3dd53b94, v227
	v_fmamk_f32 v88, v88, 0x3dd53b94, v227
	v_fmamk_f32 v89, v89, 0x3dd53b94, v227
	v_fmamk_f32 v90, v90, 0x3dd53b94, v227
	v_fmamk_f32 v91, v91, 0x3dd53b94, v227
	v_fmamk_f32 v92, v92, 0x3dd53b94, v227
	v_fmamk_f32 v93, v93, 0x3dd53b94, v227
	v_fmamk_f32 v94, v94, 0x3dd53b94, v227
	v_fmamk_f32 v95, v95, 0x3dd53b94, v227
	v_fmamk_f32 v96, v96, 0x3dd53b94, v227
	v_fmamk_f32 v97, v97, 0x3dd53b94, v227
	v_exp_f32_e32 v168, v82
	v_exp_f32_e32 v183, v83
	v_exp_f32_e32 v169, v84
	v_exp_f32_e32 v182, v85
	v_exp_f32_e32 v170, v86
	v_exp_f32_e32 v181, v87
	v_exp_f32_e32 v171, v88
	v_exp_f32_e32 v180, v89
	v_exp_f32_e32 v172, v90
	v_exp_f32_e32 v179, v91
	v_exp_f32_e32 v173, v92
	v_exp_f32_e32 v178, v93
	v_exp_f32_e32 v174, v94
	v_exp_f32_e32 v177, v95
	v_exp_f32_e32 v175, v96
	v_exp_f32_e32 v176, v97
	v_fmamk_f32 v242, v66, 0x3dd53b94, v227
	v_fmamk_f32 v243, v67, 0x3dd53b94, v227
	v_fmamk_f32 v244, v68, 0x3dd53b94, v227
	v_fmamk_f32 v245, v69, 0x3dd53b94, v227
	v_fmamk_f32 v246, v70, 0x3dd53b94, v227
	v_fmamk_f32 v229, v71, 0x3dd53b94, v227
	v_fmamk_f32 v230, v72, 0x3dd53b94, v227
	v_fmamk_f32 v231, v73, 0x3dd53b94, v227
	v_fmamk_f32 v238, v74, 0x3dd53b94, v227
	v_fmamk_f32 v239, v75, 0x3dd53b94, v227
	v_fmamk_f32 v240, v76, 0x3dd53b94, v227
	v_fmamk_f32 v241, v77, 0x3dd53b94, v227
	v_fmamk_f32 v228, v78, 0x3dd53b94, v227
	v_fmamk_f32 v247, v79, 0x3dd53b94, v227
	v_fmamk_f32 v248, v80, 0x3dd53b94, v227
	v_fmac_f32_e32 v227, 0x3dd53b94, v81
	s_setprio 0
	s_branch .Lblk0_j

.LBB0_1402:
	s_cmp_eq_u32 s100, 0
	s_cbranch_scc1 .Lblk1_a
	s_waitcnt lgkmcnt(0)
	s_barrier
	s_setprio 2
	v_cndmask_b32_e64 v176, v148, v224, s[40:41]
	v_mul_f32_e32 v150, 0xbdd53b94, v176
	v_mov_b32_e32 v151, v150
	v_fmamk_f32 v82, v82, 0x3dd53b94, v150
	v_fmamk_f32 v83, v83, 0x3dd53b94, v150
	v_fmamk_f32 v84, v84, 0x3dd53b94, v150
	v_fmamk_f32 v85, v85, 0x3dd53b94, v150
	v_fmamk_f32 v86, v86, 0x3dd53b94, v150
	v_fmamk_f32 v87, v87, 0x3dd53b94, v150
	v_fmamk_f32 v88, v88, 0x3dd53b94, v150
	v_fmamk_f32 v89, v89, 0x3dd53b94, v150
	v_fmamk_f32 v90, v90, 0x3dd53b94, v150
	v_fmamk_f32 v91, v91, 0x3dd53b94, v150
	v_fmamk_f32 v92, v92, 0x3dd53b94, v150
	v_fmamk_f32 v93, v93, 0x3dd53b94, v150
	v_fmamk_f32 v94, v94, 0x3dd53b94, v150
	v_fmamk_f32 v95, v95, 0x3dd53b94, v150
	v_fmamk_f32 v96, v96, 0x3dd53b94, v150
	v_fmac_f32_e32 v151, 0x3dd53b94, v97
	v_exp_f32_e32 v168, v82
	v_exp_f32_e32 v181, v83
	v_exp_f32_e32 v169, v84
	v_exp_f32_e32 v180, v85
	v_exp_f32_e32 v170, v86
	v_exp_f32_e32 v179, v87
	v_exp_f32_e32 v171, v88
	v_exp_f32_e32 v178, v89
	v_exp_f32_e32 v172, v90
	v_exp_f32_e32 v177, v91
	v_exp_f32_e32 v173, v92
	v_exp_f32_e32 v175, v93
	v_exp_f32_e32 v166, v94
	v_exp_f32_e32 v174, v95
	v_exp_f32_e32 v165, v96
	v_exp_f32_e32 v167, v151
	v_pk_fma_f32 v[160:161], v[66:67], s[34:35], v[150:151] op_sel_hi:[1,0,0]
	v_add_f32_e32 v66, v221, v222
	v_fmac_f32_e32 v66, v217, v210
	v_add_f32_e32 v210, v227, v228
	s_addk_i32 s26, 0x80
	s_add_i32 s0, s0, 2
	v_pk_fma_f32 v[158:159], v[68:69], s[34:35], v[150:151] op_sel_hi:[1,0,0]
	v_pk_fma_f32 v[154:155], v[70:71], s[34:35], v[150:151] op_sel_hi:[1,0,0]
	v_pk_fma_f32 v[152:153], v[72:73], s[34:35], v[150:151] op_sel_hi:[1,0,0]
	v_pk_fma_f32 v[148:149], v[74:75], s[34:35], v[150:151] op_sel_hi:[1,0,0]
	v_pk_fma_f32 v[162:163], v[76:77], s[34:35], v[150:151] op_sel_hi:[1,0,0]
	v_pk_fma_f32 v[156:157], v[78:79], s[34:35], v[150:151] op_sel_hi:[1,0,0]
	v_pk_fma_f32 v[150:151], v[80:81], s[34:35], v[150:151] op_sel_hi:[1,0,0]
	v_fmac_f32_e32 v210, v66, v223
	s_cmp_lt_u32 s0, s25
	v_add_u32_e32 v189, 0xffffff80, v189
	s_setprio 0
	s_branch .Lblk1_j
